# baseline (speedup 1.0000x reference)
.Lkv_k_body_ctx:
	v_lshlrev_b32_e32 v132, s84, v130
	v_add_u32_e32 v134, v230, v231
	v_lshl_add_u32 v132, v134, 1, v132
	s_lshl_b32 s58, 16, s84
	s_mul_i32 s59, s58, 5
	v_cvt_pk_bf16_f32 v136, v126, v127
	v_cvt_pk_bf16_f32 v138, v122, v123
	v_cvt_pk_bf16_f32 v137, v128, v129
	v_cvt_pk_bf16_f32 v139, v124, v125
	v_permlane16_swap_b32_e32 v136, v138
	s_nop 0
	v_permlane16_swap_b32_e32 v137, v139
	global_store_dwordx4 v132, v[136:139], s[6:7] offset:0
	global_store_dwordx4 v133, v[126:129], s[8:9] offset:0
	global_store_dwordx4 v133, v[122:125], s[8:9] offset:64
	v_cvt_pk_bf16_f32 v140, v94, v95
	v_cvt_pk_bf16_f32 v142, v90, v91
	v_cvt_pk_bf16_f32 v141, v96, v97
	v_cvt_pk_bf16_f32 v143, v92, v93
	v_permlane16_swap_b32_e32 v140, v142
	s_nop 0
	v_permlane16_swap_b32_e32 v141, v143
	global_store_dwordx4 v132, v[140:143], s[6:7] offset:256
	global_store_dwordx4 v133, v[94:97], s[8:9] offset:512
	global_store_dwordx4 v133, v[90:93], s[8:9] offset:576
	s_add_u32 s6, s6, s58
	s_addc_u32 s7, s7, 0
	s_add_u32 s8, s8, s70
	s_addc_u32 s9, s9, 0
	v_cvt_pk_bf16_f32 v144, v118, v119
	v_cvt_pk_bf16_f32 v146, v114, v115
	v_cvt_pk_bf16_f32 v145, v120, v121
	v_cvt_pk_bf16_f32 v147, v116, v117
	v_permlane16_swap_b32_e32 v144, v146
	s_nop 0
	v_permlane16_swap_b32_e32 v145, v147
	global_store_dwordx4 v132, v[144:147], s[6:7] offset:0
	global_store_dwordx4 v133, v[118:121], s[8:9] offset:0
	global_store_dwordx4 v133, v[114:117], s[8:9] offset:64
	v_cvt_pk_bf16_f32 v148, v86, v87
	v_cvt_pk_bf16_f32 v150, v82, v83
	v_cvt_pk_bf16_f32 v149, v88, v89
	v_cvt_pk_bf16_f32 v151, v84, v85
	v_permlane16_swap_b32_e32 v148, v150
	s_nop 0
	v_permlane16_swap_b32_e32 v149, v151
	global_store_dwordx4 v132, v[148:151], s[6:7] offset:256
	global_store_dwordx4 v133, v[86:89], s[8:9] offset:512
	global_store_dwordx4 v133, v[82:85], s[8:9] offset:576
	s_add_u32 s6, s6, s58
	s_addc_u32 s7, s7, 0
	s_add_u32 s8, s8, s70
	s_addc_u32 s9, s9, 0
	v_cvt_pk_bf16_f32 v152, v110, v111
	v_cvt_pk_bf16_f32 v154, v106, v107
	v_cvt_pk_bf16_f32 v153, v112, v113
	v_cvt_pk_bf16_f32 v155, v108, v109
	v_permlane16_swap_b32_e32 v152, v154
	s_nop 0
	v_permlane16_swap_b32_e32 v153, v155
	global_store_dwordx4 v132, v[152:155], s[6:7] offset:0
	global_store_dwordx4 v133, v[110:113], s[8:9] offset:0
	global_store_dwordx4 v133, v[106:109], s[8:9] offset:64
	v_cvt_pk_bf16_f32 v156, v78, v79
	v_cvt_pk_bf16_f32 v158, v74, v75
	v_cvt_pk_bf16_f32 v157, v80, v81
	v_cvt_pk_bf16_f32 v159, v76, v77
	v_permlane16_swap_b32_e32 v156, v158
	s_nop 0
	v_permlane16_swap_b32_e32 v157, v159
	global_store_dwordx4 v132, v[156:159], s[6:7] offset:256
	global_store_dwordx4 v133, v[78:81], s[8:9] offset:512
	global_store_dwordx4 v133, v[74:77], s[8:9] offset:576
	s_add_u32 s6, s6, s58
	s_addc_u32 s7, s7, 0
	s_add_u32 s8, s8, s70
	s_addc_u32 s9, s9, 0
	v_cvt_pk_bf16_f32 v160, v102, v103
	v_cvt_pk_bf16_f32 v162, v98, v99
	v_cvt_pk_bf16_f32 v161, v104, v105
	v_cvt_pk_bf16_f32 v163, v100, v101
	v_permlane16_swap_b32_e32 v160, v162
	s_nop 0
	v_permlane16_swap_b32_e32 v161, v163
	global_store_dwordx4 v132, v[160:163], s[6:7] offset:0
	global_store_dwordx4 v133, v[102:105], s[8:9] offset:0
	global_store_dwordx4 v133, v[98:101], s[8:9] offset:64
	v_cvt_pk_bf16_f32 v164, v70, v71
	v_cvt_pk_bf16_f32 v166, v66, v67
	v_cvt_pk_bf16_f32 v165, v72, v73
	v_cvt_pk_bf16_f32 v167, v68, v69
	v_permlane16_swap_b32_e32 v164, v166
	s_nop 0
	v_permlane16_swap_b32_e32 v165, v167
	global_store_dwordx4 v132, v[164:167], s[6:7] offset:256
	global_store_dwordx4 v133, v[70:73], s[8:9] offset:512
	global_store_dwordx4 v133, v[66:69], s[8:9] offset:576
	s_add_u32 s6, s6, s59
	s_addc_u32 s7, s7, 0
	s_add_u32 s8, s8, s71
	s_addc_u32 s9, s9, 0
	v_cvt_pk_bf16_f32 v136, v62, v63
	v_cvt_pk_bf16_f32 v138, v58, v59
	v_cvt_pk_bf16_f32 v137, v64, v65
	v_cvt_pk_bf16_f32 v139, v60, v61
	v_permlane16_swap_b32_e32 v136, v138
	s_nop 0
	v_permlane16_swap_b32_e32 v137, v139
	global_store_dwordx4 v132, v[136:139], s[6:7] offset:0
	global_store_dwordx4 v133, v[62:65], s[8:9] offset:0
	global_store_dwordx4 v133, v[58:61], s[8:9] offset:64
	v_cvt_pk_bf16_f32 v140, v30, v31
	v_cvt_pk_bf16_f32 v142, v26, v27
	v_cvt_pk_bf16_f32 v141, v32, v33
	v_cvt_pk_bf16_f32 v143, v28, v29
	v_permlane16_swap_b32_e32 v140, v142
	s_nop 0
	v_permlane16_swap_b32_e32 v141, v143
	global_store_dwordx4 v132, v[140:143], s[6:7] offset:256
	global_store_dwordx4 v133, v[30:33], s[8:9] offset:512
	global_store_dwordx4 v133, v[26:29], s[8:9] offset:576
	s_add_u32 s6, s6, s58
	s_addc_u32 s7, s7, 0
	s_add_u32 s8, s8, s70
	s_addc_u32 s9, s9, 0
	v_cvt_pk_bf16_f32 v144, v54, v55
	v_cvt_pk_bf16_f32 v146, v50, v51
	v_cvt_pk_bf16_f32 v145, v56, v57
	v_cvt_pk_bf16_f32 v147, v52, v53
	v_permlane16_swap_b32_e32 v144, v146
	s_nop 0
	v_permlane16_swap_b32_e32 v145, v147
	global_store_dwordx4 v132, v[144:147], s[6:7] offset:0
	global_store_dwordx4 v133, v[54:57], s[8:9] offset:0
	global_store_dwordx4 v133, v[50:53], s[8:9] offset:64
	v_cvt_pk_bf16_f32 v148, v22, v23
	v_cvt_pk_bf16_f32 v150, v18, v19
	v_cvt_pk_bf16_f32 v149, v24, v25
	v_cvt_pk_bf16_f32 v151, v20, v21
	v_permlane16_swap_b32_e32 v148, v150
	s_nop 0
	v_permlane16_swap_b32_e32 v149, v151
	global_store_dwordx4 v132, v[148:151], s[6:7] offset:256
	global_store_dwordx4 v133, v[22:25], s[8:9] offset:512
	global_store_dwordx4 v133, v[18:21], s[8:9] offset:576
	s_add_u32 s6, s6, s58
	s_addc_u32 s7, s7, 0
	s_add_u32 s8, s8, s70
	s_addc_u32 s9, s9, 0
	v_cvt_pk_bf16_f32 v152, v46, v47
	v_cvt_pk_bf16_f32 v154, v42, v43
	v_cvt_pk_bf16_f32 v153, v48, v49
	v_cvt_pk_bf16_f32 v155, v44, v45
	v_permlane16_swap_b32_e32 v152, v154
	s_nop 0
	v_permlane16_swap_b32_e32 v153, v155
	global_store_dwordx4 v132, v[152:155], s[6:7] offset:0
	global_store_dwordx4 v133, v[46:49], s[8:9] offset:0
	global_store_dwordx4 v133, v[42:45], s[8:9] offset:64
	v_cvt_pk_bf16_f32 v156, v14, v15
	v_cvt_pk_bf16_f32 v158, v10, v11
	v_cvt_pk_bf16_f32 v157, v16, v17
	v_cvt_pk_bf16_f32 v159, v12, v13
	v_permlane16_swap_b32_e32 v156, v158
	s_nop 0
	v_permlane16_swap_b32_e32 v157, v159
	global_store_dwordx4 v132, v[156:159], s[6:7] offset:256
	global_store_dwordx4 v133, v[14:17], s[8:9] offset:512
	global_store_dwordx4 v133, v[10:13], s[8:9] offset:576
	s_add_u32 s6, s6, s58
	s_addc_u32 s7, s7, 0
	s_add_u32 s8, s8, s70
	s_addc_u32 s9, s9, 0
	v_cvt_pk_bf16_f32 v160, v38, v39
	v_cvt_pk_bf16_f32 v162, v34, v35
	v_cvt_pk_bf16_f32 v161, v40, v41
	v_cvt_pk_bf16_f32 v163, v36, v37
	v_permlane16_swap_b32_e32 v160, v162
	s_nop 0
	v_permlane16_swap_b32_e32 v161, v163
	global_store_dwordx4 v132, v[160:163], s[6:7] offset:0
	global_store_dwordx4 v133, v[38:41], s[8:9] offset:0
	global_store_dwordx4 v133, v[34:37], s[8:9] offset:64
	v_cvt_pk_bf16_f32 v164, v6, v7
	v_cvt_pk_bf16_f32 v166, v2, v3
	v_cvt_pk_bf16_f32 v165, v8, v9
	v_cvt_pk_bf16_f32 v167, v4, v5
	v_permlane16_swap_b32_e32 v164, v166
	s_nop 0
	v_permlane16_swap_b32_e32 v165, v167
	global_store_dwordx4 v132, v[164:167], s[6:7] offset:256
	global_store_dwordx4 v133, v[6:9], s[8:9] offset:512
	global_store_dwordx4 v133, v[2:5], s[8:9] offset:576
	s_branch .LBB0_247
.Lkv_k_body_lat:
	v_lshlrev_b32_e32 v132, s84, v130
	v_add_u32_e32 v134, v230, v231
	v_lshl_add_u32 v132, v134, 1, v132
	s_lshl_b32 s58, 16, s84
	s_mul_i32 s59, s58, 5
	v_cvt_pk_bf16_f32 v136, v126, v127
	v_cvt_pk_bf16_f32 v138, v122, v123
	v_cvt_pk_bf16_f32 v137, v128, v129
	v_cvt_pk_bf16_f32 v139, v124, v125
	v_permlane16_swap_b32_e32 v136, v138
	s_nop 0
	v_permlane16_swap_b32_e32 v137, v139
	global_store_dwordx4 v132, v[136:139], s[6:7] offset:0
	v_cvt_pk_bf16_f32 v140, v94, v95
	v_cvt_pk_bf16_f32 v142, v90, v91
	v_cvt_pk_bf16_f32 v141, v96, v97
	v_cvt_pk_bf16_f32 v143, v92, v93
	v_permlane16_swap_b32_e32 v140, v142
	s_nop 0
	v_permlane16_swap_b32_e32 v141, v143
	global_store_dwordx4 v132, v[140:143], s[6:7] offset:256
	s_add_u32 s6, s6, s58
	s_addc_u32 s7, s7, 0
	v_cvt_pk_bf16_f32 v144, v118, v119
	v_cvt_pk_bf16_f32 v146, v114, v115
	v_cvt_pk_bf16_f32 v145, v120, v121
	v_cvt_pk_bf16_f32 v147, v116, v117
	v_permlane16_swap_b32_e32 v144, v146
	s_nop 0
	v_permlane16_swap_b32_e32 v145, v147
	global_store_dwordx4 v132, v[144:147], s[6:7] offset:0
	v_cvt_pk_bf16_f32 v148, v86, v87
	v_cvt_pk_bf16_f32 v150, v82, v83
	v_cvt_pk_bf16_f32 v149, v88, v89
	v_cvt_pk_bf16_f32 v151, v84, v85
	v_permlane16_swap_b32_e32 v148, v150
	s_nop 0
	v_permlane16_swap_b32_e32 v149, v151
	global_store_dwordx4 v132, v[148:151], s[6:7] offset:256
	s_add_u32 s6, s6, s58
	s_addc_u32 s7, s7, 0
	v_cvt_pk_bf16_f32 v152, v110, v111
	v_cvt_pk_bf16_f32 v154, v106, v107
	v_cvt_pk_bf16_f32 v153, v112, v113
	v_cvt_pk_bf16_f32 v155, v108, v109
	v_permlane16_swap_b32_e32 v152, v154
	s_nop 0
	v_permlane16_swap_b32_e32 v153, v155
	global_store_dwordx4 v132, v[152:155], s[6:7] offset:0
	v_cvt_pk_bf16_f32 v156, v78, v79
	v_cvt_pk_bf16_f32 v158, v74, v75
	v_cvt_pk_bf16_f32 v157, v80, v81
	v_cvt_pk_bf16_f32 v159, v76, v77
	v_permlane16_swap_b32_e32 v156, v158
	s_nop 0
	v_permlane16_swap_b32_e32 v157, v159
	global_store_dwordx4 v132, v[156:159], s[6:7] offset:256
	s_add_u32 s6, s6, s58
	s_addc_u32 s7, s7, 0
	v_cvt_pk_bf16_f32 v160, v102, v103
	v_cvt_pk_bf16_f32 v162, v98, v99
	v_cvt_pk_bf16_f32 v161, v104, v105
	v_cvt_pk_bf16_f32 v163, v100, v101
	v_permlane16_swap_b32_e32 v160, v162
	s_nop 0
	v_permlane16_swap_b32_e32 v161, v163
	global_store_dwordx4 v132, v[160:163], s[6:7] offset:0
	v_cvt_pk_bf16_f32 v164, v70, v71
	v_cvt_pk_bf16_f32 v166, v66, v67
	v_cvt_pk_bf16_f32 v165, v72, v73
	v_cvt_pk_bf16_f32 v167, v68, v69
	v_permlane16_swap_b32_e32 v164, v166
	s_nop 0
	v_permlane16_swap_b32_e32 v165, v167
	global_store_dwordx4 v132, v[164:167], s[6:7] offset:256
	s_add_u32 s6, s6, s59
	s_addc_u32 s7, s7, 0
	v_cvt_pk_bf16_f32 v136, v62, v63
	v_cvt_pk_bf16_f32 v138, v58, v59
	v_cvt_pk_bf16_f32 v137, v64, v65
	v_cvt_pk_bf16_f32 v139, v60, v61
	v_permlane16_swap_b32_e32 v136, v138
	s_nop 0
	v_permlane16_swap_b32_e32 v137, v139
	global_store_dwordx4 v132, v[136:139], s[6:7] offset:0
	v_cvt_pk_bf16_f32 v140, v30, v31
	v_cvt_pk_bf16_f32 v142, v26, v27
	v_cvt_pk_bf16_f32 v141, v32, v33
	v_cvt_pk_bf16_f32 v143, v28, v29
	v_permlane16_swap_b32_e32 v140, v142
	s_nop 0
	v_permlane16_swap_b32_e32 v141, v143
	global_store_dwordx4 v132, v[140:143], s[6:7] offset:256
	s_add_u32 s6, s6, s58
	s_addc_u32 s7, s7, 0
	v_cvt_pk_bf16_f32 v144, v54, v55
	v_cvt_pk_bf16_f32 v146, v50, v51
	v_cvt_pk_bf16_f32 v145, v56, v57
	v_cvt_pk_bf16_f32 v147, v52, v53
	v_permlane16_swap_b32_e32 v144, v146
	s_nop 0
	v_permlane16_swap_b32_e32 v145, v147
	global_store_dwordx4 v132, v[144:147], s[6:7] offset:0
	v_cvt_pk_bf16_f32 v148, v22, v23
	v_cvt_pk_bf16_f32 v150, v18, v19
	v_cvt_pk_bf16_f32 v149, v24, v25
	v_cvt_pk_bf16_f32 v151, v20, v21
	v_permlane16_swap_b32_e32 v148, v150
	s_nop 0
	v_permlane16_swap_b32_e32 v149, v151
	global_store_dwordx4 v132, v[148:151], s[6:7] offset:256
	s_add_u32 s6, s6, s58
	s_addc_u32 s7, s7, 0
	v_cvt_pk_bf16_f32 v152, v46, v47
	v_cvt_pk_bf16_f32 v154, v42, v43
	v_cvt_pk_bf16_f32 v153, v48, v49
	v_cvt_pk_bf16_f32 v155, v44, v45
	v_permlane16_swap_b32_e32 v152, v154
	s_nop 0
	v_permlane16_swap_b32_e32 v153, v155
	global_store_dwordx4 v132, v[152:155], s[6:7] offset:0
	v_cvt_pk_bf16_f32 v156, v14, v15
	v_cvt_pk_bf16_f32 v158, v10, v11
	v_cvt_pk_bf16_f32 v157, v16, v17
	v_cvt_pk_bf16_f32 v159, v12, v13
	v_permlane16_swap_b32_e32 v156, v158
	s_nop 0
	v_permlane16_swap_b32_e32 v157, v159
	global_store_dwordx4 v132, v[156:159], s[6:7] offset:256
	s_add_u32 s6, s6, s58
	s_addc_u32 s7, s7, 0
	v_cvt_pk_bf16_f32 v160, v38, v39
	v_cvt_pk_bf16_f32 v162, v34, v35
	v_cvt_pk_bf16_f32 v161, v40, v41
	v_cvt_pk_bf16_f32 v163, v36, v37
	v_permlane16_swap_b32_e32 v160, v162
	s_nop 0
	v_permlane16_swap_b32_e32 v161, v163
	global_store_dwordx4 v132, v[160:163], s[6:7] offset:0
	v_cvt_pk_bf16_f32 v164, v6, v7
	v_cvt_pk_bf16_f32 v166, v2, v3
	v_cvt_pk_bf16_f32 v165, v8, v9
	v_cvt_pk_bf16_f32 v167, v4, v5
	v_permlane16_swap_b32_e32 v164, v166
	s_nop 0
	v_permlane16_swap_b32_e32 v165, v167
	global_store_dwordx4 v132, v[164:167], s[6:7] offset:256
	s_branch .LBB0_247
